# same as previous bundle, with wait-state padding restored where hoisted LDS reads had served as MFMA/VALU hazard spacing (static hazard scan clean)
# speedup vs baseline: 1.0018x; 1.0018x over previous
.LBB0_812:
	s_or_saveexec_b64 s[0:1], s[80:81]
	v_lshlrev_b32_e32 v61, 1, v135
	s_xor_b64 exec, exec, s[0:1]
	s_cbranch_execz .LBB0_814
	v_lshl_add_u32 v40, v42, 1, 0
	v_mad_u32_u24 v51, v42, s96, v40
	v_add_u32_e32 v70, 0xfc00, v51
	ds_read2_b32 v[72:73], v70 offset0:36 offset1:72
	v_add_u32_e32 v71, 0x400, v70
	ds_read2_b32 v[76:77], v71 offset0:72 offset1:108
	v_add_u32_e32 v71, 0xf800, v51
	ds_read2_b64 v[80:83], v71 offset0:182 offset1:200
	ds_read_b96 v[84:86], v51 offset:65232
	ds_read_b96 v[88:90], v51 offset:65376
	ds_read_b128 v[92:95], v51 offset:65520
	ds_read_b128 v[96:99], v70 offset:1152
	v_cmp_eq_u32_e32 vcc, 0, v135
	ds_read_b128 v[100:103], v70 offset:1296
	s_nop 0
	v_cndmask_b32_e64 v41, 0, 1.0, vcc
	s_waitcnt lgkmcnt(7)
	v_lshlrev_b32_e32 v42, 16, v72
	ds_read_b128 v[104:107], v70 offset:1440
	v_cmp_eq_u32_e32 vcc, 1, v135
	v_lshlrev_b32_e32 v45, 16, v73
	s_waitcnt lgkmcnt(6)
	v_lshlrev_b32_e32 v46, 16, v80
	v_cndmask_b32_e64 v44, 0, 1.0, vcc
	v_cmp_eq_u32_e32 vcc, 2, v135
	v_fmac_f32_e32 v44, v41, v42
	s_nop 0
	v_cndmask_b32_e64 v42, 0, 1.0, vcc
	v_fmac_f32_e32 v42, v41, v45
	v_and_b32_e32 v45, 0xffff0000, v73
	v_cmp_eq_u32_e32 vcc, 3, v135
	v_fmac_f32_e32 v42, v44, v45
	v_lshlrev_b32_e32 v47, 16, v82
	v_cndmask_b32_e64 v45, 0, 1.0, vcc
	v_fmac_f32_e32 v45, v41, v46
	v_and_b32_e32 v46, 0xffff0000, v80
	v_fmac_f32_e32 v45, v44, v46
	v_lshlrev_b32_e32 v46, 16, v81
	v_cmp_eq_u32_e32 vcc, 4, v135
	v_fmac_f32_e32 v45, v42, v46
	s_nop 0
	v_cndmask_b32_e64 v46, 0, 1.0, vcc
	v_fmac_f32_e32 v46, v41, v47
	v_and_b32_e32 v47, 0xffff0000, v82
	ds_read_b128 v[108:111], v70 offset:1584
	v_fmac_f32_e32 v46, v44, v47
	v_lshlrev_b32_e32 v47, 16, v83
	v_fmac_f32_e32 v46, v42, v47
	v_and_b32_e32 v47, 0xffff0000, v83
	v_cmp_eq_u32_e32 vcc, 5, v135
	v_fmac_f32_e32 v46, v45, v47
	s_waitcnt lgkmcnt(6)
	v_lshlrev_b32_e32 v48, 16, v84
	v_cndmask_b32_e64 v47, 0, 1.0, vcc
	v_fmac_f32_e32 v47, v41, v48
	v_and_b32_e32 v48, 0xffff0000, v84
	v_fmac_f32_e32 v47, v44, v48
	v_lshlrev_b32_e32 v48, 16, v85
	v_fmac_f32_e32 v47, v42, v48
	v_and_b32_e32 v48, 0xffff0000, v85
	v_fmac_f32_e32 v47, v45, v48
	v_lshlrev_b32_e32 v48, 16, v86
	ds_read2_b64 v[80:83], v70 offset0:200 offset1:218
	v_cmp_eq_u32_e32 vcc, 6, v135
	v_fmac_f32_e32 v47, v46, v48
	s_waitcnt lgkmcnt(6)
	v_lshlrev_b32_e32 v50, 16, v88
	v_cndmask_b32_e64 v48, 0, 1.0, vcc
	v_fmac_f32_e32 v48, v41, v50
	v_and_b32_e32 v50, 0xffff0000, v88
	v_fmac_f32_e32 v48, v44, v50
	v_lshlrev_b32_e32 v50, 16, v89
	v_fmac_f32_e32 v48, v42, v50
	v_and_b32_e32 v50, 0xffff0000, v89
	v_fmac_f32_e32 v48, v45, v50
	v_lshlrev_b32_e32 v50, 16, v90
	v_fmac_f32_e32 v48, v46, v50
	v_and_b32_e32 v50, 0xffff0000, v90
	ds_read_b128 v[84:87], v70 offset:1728
	v_cmp_eq_u32_e32 vcc, 7, v135
	v_fmac_f32_e32 v48, v47, v50
	s_waitcnt lgkmcnt(6)
	v_lshlrev_b32_e32 v51, 16, v92
	v_cndmask_b32_e64 v50, 0, 1.0, vcc
	v_fmac_f32_e32 v50, v41, v51
	v_and_b32_e32 v51, 0xffff0000, v92
	v_fmac_f32_e32 v50, v44, v51
	v_lshlrev_b32_e32 v51, 16, v93
	v_fmac_f32_e32 v50, v42, v51
	v_and_b32_e32 v51, 0xffff0000, v93
	v_fmac_f32_e32 v50, v45, v51
	v_lshlrev_b32_e32 v51, 16, v94
	v_fmac_f32_e32 v50, v46, v51
	v_and_b32_e32 v51, 0xffff0000, v94
	v_fmac_f32_e32 v50, v47, v51
	v_lshlrev_b32_e32 v51, 16, v95
	ds_read_b128 v[88:91], v70 offset:1872
	v_cmp_eq_u32_e32 vcc, 8, v135
	v_fmac_f32_e32 v50, v48, v51
	s_waitcnt lgkmcnt(6)
	v_lshlrev_b32_e32 v53, 16, v96
	v_cndmask_b32_e64 v51, 0, 1.0, vcc
	v_fmac_f32_e32 v51, v41, v53
	v_and_b32_e32 v53, 0xffff0000, v96
	v_fmac_f32_e32 v51, v44, v53
	v_lshlrev_b32_e32 v53, 16, v97
	v_fmac_f32_e32 v51, v42, v53
	v_and_b32_e32 v53, 0xffff0000, v97
	v_fmac_f32_e32 v51, v45, v53
	v_lshlrev_b32_e32 v53, 16, v98
	v_fmac_f32_e32 v51, v46, v53
	v_and_b32_e32 v53, 0xffff0000, v98
	v_fmac_f32_e32 v51, v47, v53
	v_lshlrev_b32_e32 v53, 16, v99
	v_fmac_f32_e32 v51, v48, v53
	v_and_b32_e32 v53, 0xffff0000, v99
	ds_read_b96 v[92:94], v70 offset:1888
	v_cmp_eq_u32_e32 vcc, 9, v135
	v_fmac_f32_e32 v51, v50, v53
	s_waitcnt lgkmcnt(6)
	v_lshlrev_b32_e32 v58, 16, v100
	v_cndmask_b32_e64 v53, 0, 1.0, vcc
	v_fmac_f32_e32 v53, v41, v58
	v_and_b32_e32 v54, 0xffff0000, v100
	v_fmac_f32_e32 v53, v44, v54
	v_lshlrev_b32_e32 v54, 16, v101
	v_fmac_f32_e32 v53, v42, v54
	v_and_b32_e32 v54, 0xffff0000, v101
	v_fmac_f32_e32 v53, v45, v54
	v_lshlrev_b32_e32 v54, 16, v102
	v_fmac_f32_e32 v53, v46, v54
	v_and_b32_e32 v54, 0xffff0000, v102
	v_fmac_f32_e32 v53, v47, v54
	v_lshlrev_b32_e32 v54, 16, v103
	v_fmac_f32_e32 v53, v48, v54
	v_and_b32_e32 v54, 0xffff0000, v103
	ds_read_b128 v[96:99], v70 offset:2016
	v_fmac_f32_e32 v53, v50, v54
	v_lshlrev_b32_e32 v54, 16, v76
	v_cmp_eq_u32_e32 vcc, 10, v135
	v_fmac_f32_e32 v53, v51, v54
	s_waitcnt lgkmcnt(6)
	v_lshlrev_b32_e32 v55, 16, v104
	v_cndmask_b32_e64 v54, 0, 1.0, vcc
	v_fmac_f32_e32 v54, v41, v55
	v_and_b32_e32 v55, 0xffff0000, v104
	v_fmac_f32_e32 v54, v44, v55
	v_lshlrev_b32_e32 v55, 16, v105
	v_fmac_f32_e32 v54, v42, v55
	v_and_b32_e32 v55, 0xffff0000, v105
	v_fmac_f32_e32 v54, v45, v55
	v_lshlrev_b32_e32 v55, 16, v106
	v_fmac_f32_e32 v54, v46, v55
	v_and_b32_e32 v55, 0xffff0000, v106
	v_fmac_f32_e32 v54, v47, v55
	v_lshlrev_b32_e32 v55, 16, v107
	v_fmac_f32_e32 v54, v48, v55
	v_and_b32_e32 v55, 0xffff0000, v107
	v_fmac_f32_e32 v54, v50, v55
	v_lshlrev_b32_e32 v55, 16, v77
	v_fmac_f32_e32 v54, v51, v55
	v_and_b32_e32 v55, 0xffff0000, v77
	ds_read_b96 v[76:78], v70 offset:2032
	v_cmp_eq_u32_e32 vcc, 11, v135
	v_fmac_f32_e32 v54, v53, v55
	s_waitcnt lgkmcnt(6)
	v_lshlrev_b32_e32 v63, 16, v108
	v_cndmask_b32_e64 v55, 0, 1.0, vcc
	v_fmac_f32_e32 v55, v41, v63
	v_and_b32_e32 v56, 0xffff0000, v108
	v_fmac_f32_e32 v55, v44, v56
	v_lshlrev_b32_e32 v56, 16, v109
	v_fmac_f32_e32 v55, v42, v56
	v_and_b32_e32 v56, 0xffff0000, v109
	v_fmac_f32_e32 v55, v45, v56
	v_lshlrev_b32_e32 v56, 16, v110
	v_fmac_f32_e32 v55, v46, v56
	v_and_b32_e32 v56, 0xffff0000, v110
	v_fmac_f32_e32 v55, v47, v56
	v_lshlrev_b32_e32 v56, 16, v111
	v_fmac_f32_e32 v55, v48, v56
	v_and_b32_e32 v56, 0xffff0000, v111
	v_fmac_f32_e32 v55, v50, v56
	s_waitcnt lgkmcnt(5)
	v_lshlrev_b32_e32 v56, 16, v80
	v_fmac_f32_e32 v55, v51, v56
	v_and_b32_e32 v56, 0xffff0000, v80
	v_fmac_f32_e32 v55, v53, v56
	v_lshlrev_b32_e32 v56, 16, v81
	v_fmac_f32_e32 v55, v54, v56
	v_cmp_eq_u32_e32 vcc, 12, v135
	s_waitcnt lgkmcnt(4)
	v_lshlrev_b32_e32 v64, 16, v84
	v_cndmask_b32_e64 v63, 0, 1.0, vcc
	v_fmac_f32_e32 v63, v41, v64
	v_and_b32_e32 v56, 0xffff0000, v84
	v_fmac_f32_e32 v63, v44, v56
	v_lshlrev_b32_e32 v56, 16, v85
	v_fmac_f32_e32 v63, v42, v56
	v_and_b32_e32 v56, 0xffff0000, v85
	v_fmac_f32_e32 v63, v45, v56
	v_lshlrev_b32_e32 v56, 16, v86
	v_fmac_f32_e32 v63, v46, v56
	v_and_b32_e32 v56, 0xffff0000, v86
	v_fmac_f32_e32 v63, v47, v56
	v_lshlrev_b32_e32 v56, 16, v87
	v_fmac_f32_e32 v63, v48, v56
	v_and_b32_e32 v56, 0xffff0000, v87
	v_fmac_f32_e32 v63, v50, v56
	v_lshlrev_b32_e32 v56, 16, v82
	v_fmac_f32_e32 v63, v51, v56
	v_and_b32_e32 v56, 0xffff0000, v82
	v_fmac_f32_e32 v63, v53, v56
	v_lshlrev_b32_e32 v56, 16, v83
	v_fmac_f32_e32 v63, v54, v56
	v_and_b32_e32 v56, 0xffff0000, v83
	v_fmac_f32_e32 v63, v55, v56
	v_cmp_eq_u32_e32 vcc, 13, v135
	s_waitcnt lgkmcnt(3)
	v_lshlrev_b32_e32 v67, 16, v88
	v_cndmask_b32_e64 v68, 0, 1.0, vcc
	v_fmac_f32_e32 v68, v41, v67
	v_and_b32_e32 v56, 0xffff0000, v88
	v_fmac_f32_e32 v68, v44, v56
	v_lshlrev_b32_e32 v56, 16, v89
	v_fmac_f32_e32 v68, v42, v56
	v_and_b32_e32 v56, 0xffff0000, v89
	v_fmac_f32_e32 v68, v45, v56
	v_lshlrev_b32_e32 v56, 16, v90
	v_fmac_f32_e32 v68, v46, v56
	v_and_b32_e32 v56, 0xffff0000, v90
	v_fmac_f32_e32 v68, v47, v56
	v_lshlrev_b32_e32 v56, 16, v91
	v_fmac_f32_e32 v68, v48, v56
	v_and_b32_e32 v56, 0xffff0000, v91
	v_fmac_f32_e32 v68, v50, v56
	s_waitcnt lgkmcnt(2)
	v_lshlrev_b32_e32 v56, 16, v92
	v_fmac_f32_e32 v68, v51, v56
	v_and_b32_e32 v56, 0xffff0000, v92
	v_fmac_f32_e32 v68, v53, v56
	v_lshlrev_b32_e32 v56, 16, v93
	v_fmac_f32_e32 v68, v54, v56
	v_and_b32_e32 v56, 0xffff0000, v93
	v_fmac_f32_e32 v68, v55, v56
	v_lshlrev_b32_e32 v56, 16, v94
	v_fmac_f32_e32 v68, v63, v56
	v_cmp_eq_u32_e32 vcc, 14, v135
	s_waitcnt lgkmcnt(1)
	v_lshlrev_b32_e32 v49, 16, v96
	v_cndmask_b32_e64 v69, 0, 1.0, vcc
	v_fmac_f32_e32 v69, v41, v49
	v_and_b32_e32 v49, 0xffff0000, v96
	v_fmac_f32_e32 v69, v44, v49
	v_lshlrev_b32_e32 v49, 16, v97
	v_fmac_f32_e32 v69, v42, v49
	v_and_b32_e32 v49, 0xffff0000, v97
	v_fmac_f32_e32 v69, v45, v49
	v_lshlrev_b32_e32 v49, 16, v98
	v_fmac_f32_e32 v69, v46, v49
	v_and_b32_e32 v49, 0xffff0000, v98
	v_fmac_f32_e32 v69, v47, v49
	v_lshlrev_b32_e32 v49, 16, v99
	v_fmac_f32_e32 v69, v48, v49
	v_and_b32_e32 v49, 0xffff0000, v99
	v_fmac_f32_e32 v69, v50, v49
	s_waitcnt lgkmcnt(0)
	v_lshlrev_b32_e32 v49, 16, v76
	v_fmac_f32_e32 v69, v51, v49
	v_and_b32_e32 v49, 0xffff0000, v76
	v_fmac_f32_e32 v69, v53, v49
	v_lshlrev_b32_e32 v49, 16, v77
	v_fmac_f32_e32 v69, v54, v49
	v_and_b32_e32 v49, 0xffff0000, v77
	v_or_b32_e32 v56, 15, v137
	v_fmac_f32_e32 v69, v55, v49
	v_lshlrev_b32_e32 v49, 16, v78
	v_mad_u64_u32 v[64:65], s[4:5], v56, s96, v[40:41]
	v_fmac_f32_e32 v69, v63, v49
	v_and_b32_e32 v49, 0xffff0000, v78
	ds_read_b128 v[56:59], v64 offset:64512
	ds_read_b128 v[64:67], v64 offset:64528
	v_cmp_eq_u32_e32 vcc, 15, v135
	v_fmac_f32_e32 v69, v68, v49
	s_waitcnt lgkmcnt(1)
	v_lshlrev_b32_e32 v40, 16, v56
	v_cndmask_b32_e64 v49, 0, 1.0, vcc
	v_fmac_f32_e32 v49, v41, v40
	v_and_b32_e32 v40, 0xffff0000, v56
	v_fmac_f32_e32 v49, v44, v40
	v_lshlrev_b32_e32 v40, 16, v57
	v_fmac_f32_e32 v49, v42, v40
	v_and_b32_e32 v40, 0xffff0000, v57
	v_fmac_f32_e32 v49, v45, v40
	v_lshlrev_b32_e32 v40, 16, v58
	v_fmac_f32_e32 v49, v46, v40
	v_and_b32_e32 v40, 0xffff0000, v58
	v_fmac_f32_e32 v49, v47, v40
	v_lshlrev_b32_e32 v40, 16, v59
	v_fmac_f32_e32 v49, v48, v40
	v_and_b32_e32 v40, 0xffff0000, v59
	v_fmac_f32_e32 v49, v50, v40
	s_waitcnt lgkmcnt(0)
	v_lshlrev_b32_e32 v40, 16, v64
	v_fmac_f32_e32 v49, v51, v40
	v_and_b32_e32 v40, 0xffff0000, v64
	v_fmac_f32_e32 v49, v53, v40
	v_lshlrev_b32_e32 v40, 16, v65
	v_fmac_f32_e32 v49, v54, v40
	v_and_b32_e32 v40, 0xffff0000, v65
	v_fmac_f32_e32 v49, v55, v40
	v_lshlrev_b32_e32 v40, 16, v66
	v_fmac_f32_e32 v49, v63, v40
	v_and_b32_e32 v40, 0xffff0000, v66
	v_fmac_f32_e32 v49, v68, v40
	v_lshlrev_b32_e32 v40, 16, v67
	v_fmac_f32_e32 v49, v69, v40
	v_lshlrev_b32_e32 v40, 9, v139
	v_add3_u32 v40, s97, v40, v61
	ds_write_b16_d16_hi v40, v41
	v_bfe_u32 v41, v44, 16, 1
	v_add3_u32 v41, v44, v41, s93
	ds_write_b16_d16_hi v40, v41 offset:32
	v_bfe_u32 v41, v42, 16, 1
	v_add3_u32 v41, v42, v41, s93
	ds_write_b16_d16_hi v40, v41 offset:64
	v_bfe_u32 v41, v45, 16, 1
	v_add3_u32 v41, v45, v41, s93
	ds_write_b16_d16_hi v40, v41 offset:96
	v_bfe_u32 v41, v46, 16, 1
	v_add3_u32 v41, v46, v41, s93
	ds_write_b16_d16_hi v40, v41 offset:128
	v_bfe_u32 v41, v47, 16, 1
	v_add3_u32 v41, v47, v41, s93
	ds_write_b16_d16_hi v40, v41 offset:160
	v_bfe_u32 v41, v48, 16, 1
	v_add3_u32 v41, v48, v41, s93
	ds_write_b16_d16_hi v40, v41 offset:192
	v_bfe_u32 v41, v50, 16, 1
	v_add3_u32 v41, v50, v41, s93
	ds_write_b16_d16_hi v40, v41 offset:224
	v_bfe_u32 v41, v51, 16, 1
	v_add3_u32 v41, v51, v41, s93
	ds_write_b16_d16_hi v40, v41 offset:256
	v_bfe_u32 v41, v53, 16, 1
	v_add3_u32 v41, v53, v41, s93
	ds_write_b16_d16_hi v40, v41 offset:288
	v_bfe_u32 v41, v54, 16, 1
	v_add3_u32 v41, v54, v41, s93
	ds_write_b16_d16_hi v40, v41 offset:320
	v_bfe_u32 v41, v55, 16, 1
	v_add3_u32 v41, v55, v41, s93
	ds_write_b16_d16_hi v40, v41 offset:352
	v_bfe_u32 v41, v63, 16, 1
	v_add3_u32 v41, v63, v41, s93
	ds_write_b16_d16_hi v40, v41 offset:384
	v_bfe_u32 v41, v68, 16, 1
	v_add3_u32 v41, v68, v41, s93
	ds_write_b16_d16_hi v40, v41 offset:416
	v_bfe_u32 v41, v69, 16, 1
	v_add3_u32 v41, v69, v41, s93
	ds_write_b16_d16_hi v40, v41 offset:448
	v_bfe_u32 v41, v49, 16, 1
	v_add3_u32 v41, v49, v41, s93
	ds_write_b16_d16_hi v40, v41 offset:480
	s_waitcnt lgkmcnt(0)

.LBB0_1023:
	s_bitcmp1_b32 s76, 0
	s_cselect_b32 s77, 0x11400, 0
	s_add_i32 s77, s77, 0
	v_add_u32_e32 v136, s77, v96
	v_add_u32_e32 v137, v136, v76
	v_add_u32_e32 v138, s77, v98
	ds_read2st64_b64 v[140:143], v137 offset0:18 offset1:41
	ds_read_b128 v[148:151], v138 offset:11520
	v_add_u32_e32 v139, s77, v76
	v_add_u32_e32 v152, v139, v96
	ds_read2_b64 v[156:159], v152 offset1:4
	ds_read2_b64 v[160:163], v152 offset0:8 offset1:12
	v_add_u32_e32 v153, v136, v92
	ds_read2st64_b64 v[168:171], v153 offset0:18 offset1:41
	v_add_u32_e32 v154, s77, v91
	ds_read_b128 v[176:179], v154 offset:11520
	v_add_u32_e32 v155, 0x800, v152
	ds_read2_b64 v[180:183], v155 offset0:32 offset1:36
	v_add_u32_e32 v165, v136, v90
	ds_read2_b64 v[184:187], v155 offset0:40 offset1:44
	v_add_u32_e32 v155, s77, v89
	ds_read2st64_b64 v[188:191], v165 offset0:18 offset1:41
	ds_read_b128 v[192:195], v155 offset:11520
	v_cvt_pk_bf16_f32 v52, v40, v41
	v_cvt_pk_bf16_f32 v53, v42, v43
	s_waitcnt lgkmcnt(9)
	v_lshlrev_b32_e32 v64, 16, v140
	v_and_b32_e32 v65, 0xffff0000, v140
	v_lshlrev_b32_e32 v70, 16, v141
	v_and_b32_e32 v71, 0xffff0000, v141
	s_waitcnt lgkmcnt(8)
	v_pk_fma_f32 v[42:43], v[42:43], v[150:151], v[70:71]
	v_pk_fma_f32 v[40:41], v[40:41], v[148:149], v[64:65]
	v_add_u32_e32 v148, 0x1000, v152
	ds_read2_b64 v[196:199], v148 offset0:64 offset1:68
	v_cvt_pk_bf16_f32 v54, v36, v37
	v_cvt_pk_bf16_f32 v55, v38, v39
	v_cvt_pk_bf16_f32 v56, v44, v45
	v_cvt_pk_bf16_f32 v57, v46, v47
	s_waitcnt lgkmcnt(8)
	v_mfma_f32_16x16x32_bf16 v[40:43], v[156:159], v[52:55], v[40:43]
	v_add_u32_e32 v149, v136, v88
	ds_read2_b64 v[156:159], v148 offset0:72 offset1:76
	v_cvt_pk_bf16_f32 v58, v48, v49
	v_cvt_pk_bf16_f32 v59, v50, v51
	v_add_u32_e32 v136, s77, v86
	ds_read2st64_b64 v[200:203], v149 offset0:18 offset1:41
	s_waitcnt lgkmcnt(9)
	v_mfma_f32_16x16x32_bf16 v[40:43], v[160:163], v[56:59], v[40:43]
	ds_read_b128 v[160:163], v136 offset:11520
	s_waitcnt lgkmcnt(9)
	v_lshlrev_b32_e32 v60, 16, v168
	v_and_b32_e32 v61, 0xffff0000, v168
	v_lshlrev_b32_e32 v70, 16, v169
	v_and_b32_e32 v71, 0xffff0000, v169
	s_waitcnt lgkmcnt(8)
	v_pk_fma_f32 v[36:37], v[36:37], v[176:177], v[60:61]
	v_pk_fma_f32 v[38:39], v[38:39], v[178:179], v[70:71]
	v_add_u32_e32 v148, v139, v87
	ds_read2_b64 v[176:179], v148 offset1:4
	s_waitcnt lgkmcnt(8)
	v_mfma_f32_16x16x32_bf16 v[36:39], v[180:183], v[52:55], v[36:39]
	ds_read2_b64 v[180:183], v148 offset0:8 offset1:12
	ds_read_b128 v[204:207], v138 offset:23296
	s_waitcnt lgkmcnt(9)
	v_mfma_f32_16x16x32_bf16 v[36:39], v[184:187], v[56:59], v[36:39]
	v_add_u32_e32 v139, 0x2800, v152
	ds_read2_b64 v[184:187], v139 offset0:192 offset1:196
	s_waitcnt lgkmcnt(9)
	v_lshlrev_b32_e32 v70, 16, v188
	v_and_b32_e32 v71, 0xffff0000, v188
	v_lshlrev_b32_e32 v114, 16, v189
	v_and_b32_e32 v115, 0xffff0000, v189
	s_waitcnt lgkmcnt(8)
	v_pk_fma_f32 v[46:47], v[46:47], v[194:195], v[114:115]
	v_pk_fma_f32 v[44:45], v[44:45], v[192:193], v[70:71]
	ds_read2_b64 v[192:195], v139 offset0:200 offset1:204
	s_waitcnt lgkmcnt(8)
	v_mfma_f32_16x16x32_bf16 v[44:47], v[196:199], v[52:55], v[44:47]
	ds_read_b128 v[196:199], v154 offset:23296
	v_add_u32_e32 v139, 0xb800, v152
	v_add_u32_e32 v150, 0x3000, v152
	ds_read2_b64 v[208:211], v150 offset0:224 offset1:228
	s_waitcnt lgkmcnt(9)
	v_mfma_f32_16x16x32_bf16 v[44:47], v[156:159], v[56:59], v[44:47]
	ds_read2_b64 v[156:159], v150 offset0:232 offset1:236
	s_waitcnt lgkmcnt(9)
	v_lshlrev_b32_e32 v70, 16, v200
	v_and_b32_e32 v71, 0xffff0000, v200
	v_lshlrev_b32_e32 v114, 16, v201
	v_and_b32_e32 v115, 0xffff0000, v201
	s_waitcnt lgkmcnt(8)
	v_pk_fma_f32 v[50:51], v[50:51], v[162:163], v[114:115]
	v_pk_fma_f32 v[48:49], v[48:49], v[160:161], v[70:71]
	ds_read_b128 v[160:163], v155 offset:23296
	v_lshl_add_u64 v[66:67], v[82:83], 0, s[24:25]
	global_store_dwordx2 v[66:67], v[52:53], off nt
	global_store_dwordx2 v[66:67], v[54:55], off offset:32 nt
	s_waitcnt lgkmcnt(8)
	v_mfma_f32_16x16x32_bf16 v[48:51], v[176:179], v[52:55], v[48:51]
	v_add_u32_e32 v150, 0x4000, v152
	ds_read2_b64 v[176:179], v150 offset1:4
	ds_read2_b64 v[212:215], v150 offset0:8 offset1:12
	v_add_co_u32_e32 v70, vcc, s10, v66
	s_waitcnt lgkmcnt(9)
	v_mfma_f32_16x16x32_bf16 v[48:51], v[180:183], v[56:59], v[48:51]
	global_store_dwordx2 v[66:67], v[56:57], off offset:64 nt
	global_store_dwordx2 v[66:67], v[58:59], off offset:96 nt
	v_cvt_pk_bf16_f32 v52, v40, v41
	v_cvt_pk_bf16_f32 v53, v42, v43
	v_addc_co_u32_e32 v71, vcc, 0, v67, vcc
	v_cvt_pk_bf16_f32 v54, v36, v37
	v_cvt_pk_bf16_f32 v55, v38, v39
	v_cvt_pk_bf16_f32 v56, v44, v45
	v_cvt_pk_bf16_f32 v57, v46, v47
	v_cvt_pk_bf16_f32 v58, v48, v49
	v_cvt_pk_bf16_f32 v59, v50, v51
	global_store_dwordx2 v[70:71], v[52:53], off nt
	global_store_dwordx2 v[70:71], v[54:55], off offset:32 nt
	global_store_dwordx2 v[70:71], v[56:57], off offset:64 nt
	global_store_dwordx2 v[70:71], v[58:59], off offset:96 nt
	v_lshlrev_b32_e32 v70, 16, v142
	v_and_b32_e32 v71, 0xffff0000, v142
	v_lshlrev_b32_e32 v108, 16, v143
	v_and_b32_e32 v109, 0xffff0000, v143
	s_waitcnt lgkmcnt(8)
	v_pk_fma_f32 v[40:41], v[40:41], v[204:205], v[70:71]
	v_pk_fma_f32 v[42:43], v[42:43], v[206:207], v[108:109]
	ds_read_b128 v[140:143], v136 offset:23296
	v_and_b32_e32 v71, 0xffff0000, v170
	s_waitcnt lgkmcnt(8)
	v_mfma_f32_16x16x32_bf16 v[40:43], v[184:187], v[52:55], v[40:43]
	v_add_u32_e32 v150, 0x2800, v148
	ds_read2_b64 v[180:183], v150 offset0:192 offset1:196
	v_lshlrev_b32_e32 v70, 16, v170
	v_lshlrev_b32_e32 v112, 16, v171
	s_waitcnt lgkmcnt(8)
	v_mfma_f32_16x16x32_bf16 v[40:43], v[192:195], v[56:59], v[40:43]
	ds_read2_b64 v[184:187], v150 offset0:200 offset1:204
	v_and_b32_e32 v113, 0xffff0000, v171
	s_mov_b32 s78, 0x8000
	s_waitcnt lgkmcnt(8)
	v_pk_fma_f32 v[36:37], v[36:37], v[196:197], v[70:71]
	v_pk_fma_f32 v[38:39], v[38:39], v[198:199], v[112:113]
	ds_read_b128 v[168:171], v138 offset:35072
	v_and_b32_e32 v71, 0xffff0000, v190
	s_waitcnt lgkmcnt(8)
	v_mfma_f32_16x16x32_bf16 v[36:39], v[208:211], v[52:55], v[36:39]
	ds_read2st64_b64 v[192:195], v137 offset0:64 offset1:87
	v_lshlrev_b32_e32 v70, 16, v190
	v_lshlrev_b32_e32 v112, 16, v191
	s_waitcnt lgkmcnt(8)
	v_mfma_f32_16x16x32_bf16 v[36:39], v[156:159], v[56:59], v[36:39]
	v_add_u32_e32 v150, 0x5800, v152
	ds_read2_b64 v[156:159], v150 offset0:128 offset1:132
	v_and_b32_e32 v113, 0xffff0000, v191
	s_waitcnt lgkmcnt(8)
	v_pk_fma_f32 v[44:45], v[44:45], v[160:161], v[70:71]
	v_pk_fma_f32 v[46:47], v[46:47], v[162:163], v[112:113]
	ds_read2_b64 v[160:163], v150 offset0:136 offset1:140
	v_and_b32_e32 v71, 0xffff0000, v202
	s_waitcnt lgkmcnt(8)
	v_mfma_f32_16x16x32_bf16 v[44:47], v[176:179], v[52:55], v[44:47]
	ds_read_b128 v[176:179], v154 offset:35072
	v_lshlrev_b32_e32 v70, 16, v202
	v_lshlrev_b32_e32 v112, 16, v203
	s_waitcnt lgkmcnt(8)
	v_mfma_f32_16x16x32_bf16 v[44:47], v[212:215], v[56:59], v[44:47]
	ds_read2st64_b64 v[188:191], v153 offset0:64 offset1:87
	v_and_b32_e32 v113, 0xffff0000, v203
	s_waitcnt lgkmcnt(8)
	v_pk_fma_f32 v[48:49], v[48:49], v[140:141], v[70:71]
	v_pk_fma_f32 v[50:51], v[50:51], v[142:143], v[112:113]
	v_add_u32_e32 v140, 0x6000, v152
	ds_read2_b64 v[196:199], v140 offset0:160 offset1:164
	s_waitcnt lgkmcnt(8)
	v_mfma_f32_16x16x32_bf16 v[48:51], v[180:183], v[52:55], v[48:51]
	ds_read2_b64 v[180:183], v140 offset0:168 offset1:172
	v_add_co_u32_e32 v70, vcc, s11, v66
	s_waitcnt lgkmcnt(8)
	v_mfma_f32_16x16x32_bf16 v[48:51], v[184:187], v[56:59], v[48:51]
	v_cvt_pk_bf16_f32 v52, v40, v41
	v_cvt_pk_bf16_f32 v53, v42, v43
	v_addc_co_u32_e32 v71, vcc, 0, v67, vcc
	v_cvt_pk_bf16_f32 v54, v36, v37
	v_cvt_pk_bf16_f32 v55, v38, v39
	v_cvt_pk_bf16_f32 v56, v44, v45
	v_cvt_pk_bf16_f32 v57, v46, v47
	s_nop 0
	v_cvt_pk_bf16_f32 v58, v48, v49
	v_cvt_pk_bf16_f32 v59, v50, v51
	global_store_dwordx2 v[70:71], v[52:53], off nt
	global_store_dwordx2 v[70:71], v[54:55], off offset:32 nt
	global_store_dwordx2 v[70:71], v[56:57], off offset:64 nt
	global_store_dwordx2 v[70:71], v[58:59], off offset:96 nt
	ds_read_b128 v[140:143], v155 offset:35072
	ds_read2st64_b64 v[184:187], v165 offset0:64 offset1:87
	s_waitcnt lgkmcnt(8)
	v_lshlrev_b32_e32 v70, 16, v192
	v_and_b32_e32 v71, 0xffff0000, v192
	v_lshlrev_b32_e32 v112, 16, v193
	v_and_b32_e32 v113, 0xffff0000, v193
	v_pk_fma_f32 v[40:41], v[40:41], v[168:169], v[70:71]
	v_pk_fma_f32 v[42:43], v[42:43], v[170:171], v[112:113]
	v_add_u32_e32 v150, 0x6800, v152
	ds_read2_b64 v[168:171], v150 offset0:192 offset1:196
	s_waitcnt lgkmcnt(8)
	v_mfma_f32_16x16x32_bf16 v[40:43], v[156:159], v[52:55], v[40:43]
	ds_read2_b64 v[156:159], v150 offset0:200 offset1:204
	s_waitcnt lgkmcnt(8)
	v_mfma_f32_16x16x32_bf16 v[40:43], v[160:163], v[56:59], v[40:43]
	ds_read_b128 v[160:163], v136 offset:35072
	ds_read2st64_b64 v[200:203], v149 offset0:64 offset1:87
	s_nop 5
	v_cvt_pk_bf16_f32 v128, v40, v41
	v_cvt_pk_bf16_f32 v129, v42, v43
	s_waitcnt lgkmcnt(8)
	v_lshlrev_b32_e32 v70, 16, v188
	v_and_b32_e32 v71, 0xffff0000, v188
	v_lshlrev_b32_e32 v112, 16, v189
	v_and_b32_e32 v113, 0xffff0000, v189
	v_pk_fma_f32 v[36:37], v[36:37], v[176:177], v[70:71]
	v_pk_fma_f32 v[38:39], v[38:39], v[178:179], v[112:113]
	v_add_u32_e32 v150, 0x5800, v148
	ds_read2_b64 v[176:179], v150 offset0:128 offset1:132
	s_waitcnt lgkmcnt(8)
	v_mfma_f32_16x16x32_bf16 v[36:39], v[196:199], v[52:55], v[36:39]
	ds_read2_b64 v[196:199], v150 offset0:136 offset1:140
	s_waitcnt lgkmcnt(8)
	v_mfma_f32_16x16x32_bf16 v[36:39], v[180:183], v[56:59], v[36:39]
	ds_read_b128 v[180:183], v138 offset:46848
	v_add_u32_e32 v150, 0x8800, v152
	ds_read2_b64 v[204:207], v150 offset0:64 offset1:68
	s_nop 5
	v_cvt_pk_bf16_f32 v130, v36, v37
	v_cvt_pk_bf16_f32 v131, v38, v39
	s_waitcnt lgkmcnt(8)
	v_lshlrev_b32_e32 v70, 16, v184
	v_and_b32_e32 v71, 0xffff0000, v184
	v_lshlrev_b32_e32 v112, 16, v185
	v_and_b32_e32 v113, 0xffff0000, v185
	v_pk_fma_f32 v[44:45], v[44:45], v[140:141], v[70:71]
	v_pk_fma_f32 v[46:47], v[46:47], v[142:143], v[112:113]
	ds_read2_b64 v[140:143], v150 offset0:72 offset1:76
	s_waitcnt lgkmcnt(8)
	v_mfma_f32_16x16x32_bf16 v[44:47], v[168:171], v[52:55], v[44:47]
	ds_read_b128 v[168:171], v154 offset:46848
	s_waitcnt lgkmcnt(8)
	v_mfma_f32_16x16x32_bf16 v[44:47], v[156:159], v[56:59], v[44:47]
	v_add_u32_e32 v150, 0x9000, v152
	ds_read2_b64 v[156:159], v150 offset0:96 offset1:100
	ds_read2_b64 v[208:211], v150 offset0:104 offset1:108
	s_nop 5
	v_cvt_pk_bf16_f32 v132, v44, v45
	v_cvt_pk_bf16_f32 v133, v46, v47
	s_waitcnt lgkmcnt(8)
	v_lshlrev_b32_e32 v70, 16, v200
	v_and_b32_e32 v71, 0xffff0000, v200
	v_lshlrev_b32_e32 v112, 16, v201
	v_and_b32_e32 v113, 0xffff0000, v201
	v_pk_fma_f32 v[48:49], v[48:49], v[160:161], v[70:71]
	v_pk_fma_f32 v[50:51], v[50:51], v[162:163], v[112:113]
	ds_read_b128 v[160:163], v155 offset:46848
	s_waitcnt lgkmcnt(8)
	v_mfma_f32_16x16x32_bf16 v[48:51], v[176:179], v[52:55], v[48:51]
	v_add_u32_e32 v150, 0x9800, v152
	ds_read2_b64 v[176:179], v150 offset0:128 offset1:132
	s_waitcnt lgkmcnt(8)
	v_mfma_f32_16x16x32_bf16 v[108:111], v[196:199], v[56:59], v[48:51]
	s_nop 4
	v_add_co_u32_e32 v48, vcc, s33, v66
	v_lshlrev_b32_e32 v52, 16, v194
	s_nop 0
	v_addc_co_u32_e32 v49, vcc, 0, v67, vcc
	v_cvt_pk_bf16_f32 v134, v108, v109
	v_cvt_pk_bf16_f32 v135, v110, v111
	global_store_dwordx2 v[48:49], v[128:129], off nt
	global_store_dwordx2 v[48:49], v[130:131], off offset:32 nt
	global_store_dwordx2 v[48:49], v[132:133], off offset:64 nt
	global_store_dwordx2 v[48:49], v[134:135], off offset:96 nt
	ds_read2_b64 v[196:199], v150 offset0:136 offset1:140
	v_and_b32_e32 v53, 0xffff0000, v194
	v_lshlrev_b32_e32 v54, 16, v195
	v_and_b32_e32 v55, 0xffff0000, v195
	v_add_co_u32_e32 v70, vcc, s78, v66
	s_waitcnt lgkmcnt(8)
	v_pk_fma_f32 v[40:41], v[40:41], v[180:181], v[52:53]
	v_pk_fma_f32 v[42:43], v[42:43], v[182:183], v[54:55]
	v_add_u32_e32 v150, 0x8800, v148
	ds_read_b128 v[180:183], v136 offset:46848
	v_and_b32_e32 v53, 0xffff0000, v190
	s_waitcnt lgkmcnt(8)
	v_mfma_f32_16x16x32_bf16 v[40:43], v[204:207], v[128:131], v[40:43]
	ds_read2_b64 v[192:195], v150 offset0:64 offset1:68
	v_lshlrev_b32_e32 v52, 16, v190
	v_lshlrev_b32_e32 v54, 16, v191
	s_waitcnt lgkmcnt(8)
	v_mfma_f32_16x16x32_bf16 v[48:51], v[140:143], v[132:135], v[40:43]
	s_nop 2
	ds_read2_b64 v[140:143], v150 offset0:72 offset1:76
	v_and_b32_e32 v55, 0xffff0000, v191
	v_addc_co_u32_e32 v71, vcc, 0, v67, vcc
	s_add_i32 s78, s77, 0x11300
	s_waitcnt lgkmcnt(8)
	v_pk_fma_f32 v[36:37], v[36:37], v[168:169], v[52:53]
	v_pk_fma_f32 v[38:39], v[38:39], v[170:171], v[54:55]
	ds_read_b128 v[168:171], v138 offset:58624
	s_add_i32 s77, s77, 0x10a00
	s_waitcnt lgkmcnt(8)
	v_mfma_f32_16x16x32_bf16 v[36:39], v[156:159], v[128:131], v[36:39]
	ds_read_b64 v[150:151], v137 offset:56320
	s_waitcnt lgkmcnt(8)
	v_mfma_f32_16x16x32_bf16 v[56:59], v[208:211], v[132:135], v[36:39]
	s_nop 4
	ds_read2_b64 v[156:159], v139 offset1:4
	v_lshlrev_b32_e32 v40, 16, v186
	v_and_b32_e32 v41, 0xffff0000, v186
	v_lshlrev_b32_e32 v42, 16, v187
	v_and_b32_e32 v43, 0xffff0000, v187
	s_waitcnt lgkmcnt(8)
	v_pk_fma_f32 v[36:37], v[44:45], v[160:161], v[40:41]
	v_pk_fma_f32 v[38:39], v[46:47], v[162:163], v[42:43]
	ds_read2_b64 v[160:163], v139 offset0:8 offset1:12
	s_waitcnt lgkmcnt(8)
	v_mfma_f32_16x16x32_bf16 v[36:39], v[176:179], v[128:131], v[36:39]
	v_add_u32_e32 v137, s77, v96
	ds_read_b128 v[176:179], v154 offset:58624
	s_waitcnt lgkmcnt(8)
	v_mfma_f32_16x16x32_bf16 v[52:55], v[196:199], v[132:135], v[36:39]
	s_nop 3
	ds_read_b64 v[138:139], v153 offset:56320
	v_lshlrev_b32_e32 v40, 16, v202
	v_and_b32_e32 v41, 0xffff0000, v202
	v_lshlrev_b32_e32 v42, 16, v203
	v_and_b32_e32 v43, 0xffff0000, v203
	s_waitcnt lgkmcnt(8)
	v_pk_fma_f32 v[38:39], v[110:111], v[182:183], v[42:43]
	v_pk_fma_f32 v[36:37], v[108:109], v[180:181], v[40:41]
	v_add_u32_e32 v153, 0xc000, v152
	ds_read2_b64 v[180:183], v153 offset0:32 offset1:36
	s_waitcnt lgkmcnt(8)
	v_mfma_f32_16x16x32_bf16 v[36:39], v[192:195], v[128:131], v[36:39]
	ds_read2_b64 v[184:187], v153 offset0:40 offset1:44
	s_waitcnt lgkmcnt(8)
	v_mfma_f32_16x16x32_bf16 v[44:47], v[140:143], v[132:135], v[36:39]
	v_cvt_pk_bf16_f32 v40, v48, v49
	v_cvt_pk_bf16_f32 v41, v50, v51
	v_cvt_pk_bf16_f32 v42, v56, v57
	v_cvt_pk_bf16_f32 v43, v58, v59
	s_nop 0
	v_cvt_pk_bf16_f32 v36, v52, v53
	v_cvt_pk_bf16_f32 v37, v54, v55
	s_nop 0
	v_cvt_pk_bf16_f32 v38, v44, v45
	v_cvt_pk_bf16_f32 v39, v46, v47
	global_store_dwordx2 v[70:71], v[40:41], off nt
	global_store_dwordx2 v[70:71], v[42:43], off offset:32 nt
	global_store_dwordx2 v[70:71], v[36:37], off offset:64 nt
	global_store_dwordx2 v[70:71], v[38:39], off offset:96 nt
	ds_read_b128 v[140:143], v155 offset:58624
	ds_read_b64 v[154:155], v165 offset:56320
	s_waitcnt lgkmcnt(8)
	v_lshlrev_b32_e32 v70, 16, v150
	v_and_b32_e32 v71, 0xffff0000, v150
	v_lshlrev_b32_e32 v68, 16, v151
	v_and_b32_e32 v69, 0xffff0000, v151
	v_pk_fma_f32 v[50:51], v[50:51], v[170:171], v[68:69]
	v_pk_fma_f32 v[48:49], v[48:49], v[168:169], v[70:71]
	v_add_u32_e32 v150, 0xc800, v152
	ds_read2_b64 v[168:171], v150 offset0:64 offset1:68
	s_waitcnt lgkmcnt(8)
	v_mfma_f32_16x16x32_bf16 v[48:51], v[156:159], v[40:43], v[48:51]
	ds_read2_b64 v[156:159], v150 offset0:72 offset1:76
	s_waitcnt lgkmcnt(8)
	v_mfma_f32_16x16x32_bf16 v[48:51], v[160:163], v[36:39], v[48:51]
	ds_read_b128 v[160:163], v136 offset:58624
	ds_read_b64 v[150:151], v149 offset:56320
	s_waitcnt lgkmcnt(8)
	v_lshlrev_b32_e32 v110, 16, v138
	v_and_b32_e32 v111, 0xffff0000, v138
	v_lshlrev_b32_e32 v108, 16, v139
	v_and_b32_e32 v109, 0xffff0000, v139
	v_pk_fma_f32 v[58:59], v[58:59], v[178:179], v[108:109]
	v_pk_fma_f32 v[56:57], v[56:57], v[176:177], v[110:111]
	v_add_u32_e32 v136, 0xb800, v148
	ds_read2_b64 v[176:179], v136 offset1:4
	s_waitcnt lgkmcnt(8)
	v_mfma_f32_16x16x32_bf16 v[56:59], v[180:183], v[40:43], v[56:59]
	ds_read2_b64 v[180:183], v136 offset0:8 offset1:12
	s_waitcnt lgkmcnt(8)
	v_mfma_f32_16x16x32_bf16 v[56:59], v[184:187], v[36:39], v[56:59]
	v_add_u32_e32 v136, s78, v98
	v_add_u32_e32 v138, v137, v76
	ds_read_b128 v[184:187], v136
	ds_read_b64 v[166:167], v138
	s_waitcnt lgkmcnt(8)
	v_lshlrev_b32_e32 v108, 16, v154
	v_and_b32_e32 v109, 0xffff0000, v154
	v_lshlrev_b32_e32 v62, 16, v155
	v_and_b32_e32 v63, 0xffff0000, v155
	v_pk_fma_f32 v[54:55], v[54:55], v[142:143], v[62:63]
	v_pk_fma_f32 v[52:53], v[52:53], v[140:141], v[108:109]
	v_add_u32_e32 v136, 0xe000, v152
	ds_read2_b64 v[140:143], v136 offset0:192 offset1:196
	s_waitcnt lgkmcnt(8)
	v_mfma_f32_16x16x32_bf16 v[52:55], v[168:171], v[40:43], v[52:55]
	v_add_u32_e32 v138, 0xe800, v152
	ds_read2_b64 v[168:171], v136 offset0:200 offset1:204
	v_add_u32_e32 v136, v137, v92
	ds_read_b64 v[154:155], v136
	v_add_u32_e32 v136, s78, v91
	ds_read_b128 v[188:191], v136
	s_waitcnt lgkmcnt(10)
	v_mfma_f32_16x16x32_bf16 v[52:55], v[156:159], v[36:39], v[52:55]
	s_waitcnt lgkmcnt(8)
	v_lshlrev_b32_e32 v68, 16, v150
	v_and_b32_e32 v69, 0xffff0000, v150
	v_lshlrev_b32_e32 v64, 16, v151
	v_and_b32_e32 v65, 0xffff0000, v151
	v_pk_fma_f32 v[46:47], v[46:47], v[162:163], v[64:65]
	v_pk_fma_f32 v[44:45], v[44:45], v[160:161], v[68:69]
	ds_read2_b64 v[156:159], v138 offset0:224 offset1:228
	v_cvt_pk_bf16_f32 v65, v50, v51
	s_waitcnt lgkmcnt(8)
	v_mfma_f32_16x16x32_bf16 v[40:43], v[176:179], v[40:43], v[44:47]
	s_nop 2
	v_add_u32_e32 v136, 0xe000, v148
	ds_read2_b64 v[148:151], v138 offset0:232 offset1:236
	v_cvt_pk_bf16_f32 v64, v48, v49
	v_cvt_pk_bf16_f32 v60, v52, v53
	s_waitcnt lgkmcnt(8)
	v_mfma_f32_16x16x32_bf16 v[68:71], v[180:183], v[36:39], v[40:43]
	v_add_co_u32_e32 v36, vcc, s34, v66
	v_cvt_pk_bf16_f32 v66, v56, v57
	s_nop 0
	v_addc_co_u32_e32 v37, vcc, 0, v67, vcc
	v_cvt_pk_bf16_f32 v67, v58, v59
	v_cvt_pk_bf16_f32 v61, v54, v55
	s_nop 1
	v_cvt_pk_bf16_f32 v62, v68, v69
	v_cvt_pk_bf16_f32 v63, v70, v71
	global_store_dwordx2 v[36:37], v[64:65], off nt
	global_store_dwordx2 v[36:37], v[66:67], off offset:32 nt
	global_store_dwordx2 v[36:37], v[60:61], off offset:64 nt
	global_store_dwordx2 v[36:37], v[62:63], off offset:96 nt
	v_add_u32_e32 v138, v137, v90
	ds_read_b64 v[160:161], v138
	v_add_u32_e32 v138, s78, v89
	ds_read_b128 v[176:179], v138
	s_waitcnt lgkmcnt(8)
	v_lshlrev_b32_e32 v42, 16, v166
	v_and_b32_e32 v43, 0xffff0000, v166
	v_lshlrev_b32_e32 v40, 16, v167
	v_and_b32_e32 v41, 0xffff0000, v167
	v_pk_fma_f32 v[38:39], v[50:51], v[186:187], v[40:41]
	v_pk_fma_f32 v[36:37], v[48:49], v[184:185], v[42:43]
	v_add_u32_e32 v138, 0xf800, v152
	ds_read2_b64 v[180:183], v138 offset1:4
	s_waitcnt lgkmcnt(8)
	v_mfma_f32_16x16x32_bf16 v[36:39], v[140:143], v[64:67], v[36:39]
	ds_read2_b64 v[140:143], v138 offset0:8 offset1:12
	v_add_u32_e32 v138, v137, v88
	ds_read_b64 v[152:153], v138
	s_waitcnt lgkmcnt(9)
	v_mfma_f32_16x16x32_bf16 v[40:43], v[168:171], v[60:63], v[36:39]
	s_nop 2
	v_add_u32_e32 v137, s78, v86
	ds_read_b128 v[168:171], v137
	s_waitcnt lgkmcnt(9)
	v_lshlrev_b32_e32 v46, 16, v154
	v_and_b32_e32 v47, 0xffff0000, v154
	v_lshlrev_b32_e32 v44, 16, v155
	v_and_b32_e32 v45, 0xffff0000, v155
	s_waitcnt lgkmcnt(8)
	v_pk_fma_f32 v[38:39], v[58:59], v[190:191], v[44:45]
	v_pk_fma_f32 v[36:37], v[56:57], v[188:189], v[46:47]
	ds_read2_b64 v[184:187], v136 offset0:192 offset1:196
	s_waitcnt lgkmcnt(8)
	v_mfma_f32_16x16x32_bf16 v[36:39], v[156:159], v[64:67], v[36:39]
	ds_read2_b64 v[156:159], v136 offset0:200 offset1:204
	s_waitcnt lgkmcnt(8)
	v_mfma_f32_16x16x32_bf16 v[36:39], v[148:151], v[60:63], v[36:39]
	s_waitcnt lgkmcnt(7)
	v_lshlrev_b32_e32 v50, 16, v160
	v_and_b32_e32 v51, 0xffff0000, v160
	v_lshlrev_b32_e32 v48, 16, v161
	v_and_b32_e32 v49, 0xffff0000, v161
	s_waitcnt lgkmcnt(6)
	v_pk_fma_f32 v[44:45], v[52:53], v[176:177], v[50:51]
	v_pk_fma_f32 v[46:47], v[54:55], v[178:179], v[48:49]
	s_waitcnt lgkmcnt(5)
	s_nop 0
	v_mfma_f32_16x16x32_bf16 v[44:47], v[180:183], v[64:67], v[44:47]
	s_waitcnt lgkmcnt(4)
	v_mfma_f32_16x16x32_bf16 v[44:47], v[140:143], v[60:63], v[44:47]
	s_waitcnt lgkmcnt(3)
	v_lshlrev_b32_e32 v54, 16, v152
	v_and_b32_e32 v55, 0xffff0000, v152
	v_lshlrev_b32_e32 v52, 16, v153
	v_and_b32_e32 v53, 0xffff0000, v153
	s_waitcnt lgkmcnt(2)
	v_pk_fma_f32 v[50:51], v[70:71], v[170:171], v[52:53]
	v_pk_fma_f32 v[48:49], v[68:69], v[168:169], v[54:55]
	s_waitcnt lgkmcnt(1)
	s_nop 0
	v_mfma_f32_16x16x32_bf16 v[48:51], v[184:187], v[64:67], v[48:51]
	s_waitcnt lgkmcnt(0)
	v_mfma_f32_16x16x32_bf16 v[48:51], v[156:159], v[60:63], v[48:51]

.LBB0_1030:
	v_or_b32_e32 v0, s74, v105
	v_lshlrev_b32_e32 v72, 1, v0
	v_lshlrev_b32_e32 v22, 1, v104
	s_and_saveexec_b64 s[4:5], s[0:1]
	s_cbranch_execz .LBB0_1032
	v_add_u32_e32 v68, 0, v76
	v_add_u32_e32 v136, v68, v96
	v_add_u32_e32 v137, 0, v96
	ds_read2_b64 v[140:143], v136 offset1:4
	v_add_u32_e32 v138, v137, v76
	ds_read2st64_b64 v[148:151], v138 offset0:18 offset1:41
	v_add_u32_e32 v139, 0, v98
	ds_read_b128 v[152:155], v139 offset:11520
	ds_read_b128 v[156:159], v139 offset:35072
	ds_read2_b64 v[160:163], v136 offset0:8 offset1:12
	v_add_u32_e32 v165, 0x800, v136
	ds_read2_b64 v[168:171], v165 offset0:32 offset1:36
	v_add_u32_e32 v166, v137, v92
	ds_read2st64_b64 v[176:179], v166 offset0:18 offset1:41
	v_add_u32_e32 v167, 0, v91
	ds_read_b128 v[180:183], v167 offset:11520
	ds_read2_b64 v[184:187], v165 offset0:40 offset1:44
	v_add_u32_e32 v165, 0x1000, v136
	v_add_u32_e32 v172, v137, v90
	ds_read2_b64 v[188:191], v165 offset0:64 offset1:68
	ds_read2st64_b64 v[192:195], v172 offset0:18 offset1:41
	v_add_u32_e32 v173, 0, v89
	ds_read_b128 v[196:199], v167 offset:35072
	ds_read_b128 v[200:203], v173 offset:11520
	s_waitcnt lgkmcnt(11)
	v_lshlrev_b32_e32 v24, 16, v148
	v_and_b32_e32 v25, 0xffff0000, v148
	v_lshlrev_b32_e32 v6, 16, v149
	v_and_b32_e32 v7, 0xffff0000, v149
	v_cvt_pk_bf16_f32 v0, v40, v41
	v_cvt_pk_bf16_f32 v1, v42, v43
	v_cvt_pk_bf16_f32 v2, v36, v37
	v_cvt_pk_bf16_f32 v3, v38, v39
	s_waitcnt lgkmcnt(10)
	v_pk_fma_f32 v[12:13], v[42:43], v[154:155], v[6:7]
	v_pk_fma_f32 v[10:11], v[40:41], v[152:153], v[24:25]
	ds_read2_b64 v[152:155], v165 offset0:72 offset1:76
	s_nop 0
	v_mfma_f32_16x16x32_bf16 v[10:13], v[140:143], v[0:3], v[10:13]
	v_cvt_pk_bf16_f32 v4, v44, v45
	v_cvt_pk_bf16_f32 v5, v46, v47
	v_cvt_pk_bf16_f32 v6, v48, v49
	v_cvt_pk_bf16_f32 v7, v50, v51
	v_add_u32_e32 v140, v137, v88
	ds_read2st64_b64 v[204:207], v140 offset0:18 offset1:41
	s_waitcnt lgkmcnt(10)
	v_mfma_f32_16x16x32_bf16 v[10:13], v[160:163], v[4:7], v[10:13]
	v_add_u32_e32 v137, 0, v86
	ds_read_b128 v[160:163], v173 offset:35072
	ds_read_b128 v[208:211], v137 offset:11520
	s_waitcnt lgkmcnt(10)
	v_lshlrev_b32_e32 v24, 16, v176
	v_and_b32_e32 v25, 0xffff0000, v176
	v_lshlrev_b32_e32 v14, 16, v177
	v_and_b32_e32 v15, 0xffff0000, v177
	s_waitcnt lgkmcnt(9)
	v_pk_fma_f32 v[20:21], v[38:39], v[182:183], v[14:15]
	v_pk_fma_f32 v[18:19], v[36:37], v[180:181], v[24:25]
	v_lshl_add_u64 v[14:15], s[62:63], 0, v[72:73]
	v_mov_b32_e32 v23, v73
	v_mfma_f32_16x16x32_bf16 v[18:21], v[168:171], v[0:3], v[18:21]
	v_lshl_add_u64 v[14:15], v[14:15], 0, v[22:23]
	s_waitcnt lgkmcnt(8)
	v_mfma_f32_16x16x32_bf16 v[18:21], v[184:187], v[4:7], v[18:21]
	s_waitcnt lgkmcnt(6)
	v_lshlrev_b32_e32 v24, 16, v192
	v_and_b32_e32 v25, 0xffff0000, v192
	v_lshlrev_b32_e32 v34, 16, v193
	v_and_b32_e32 v35, 0xffff0000, v193
	s_waitcnt lgkmcnt(4)
	v_pk_fma_f32 v[40:41], v[46:47], v[202:203], v[34:35]
	v_pk_fma_f32 v[38:39], v[44:45], v[200:201], v[24:25]
	v_add_u32_e32 v87, v68, v87
	s_nop 0
	v_mfma_f32_16x16x32_bf16 v[38:41], v[188:191], v[0:3], v[38:41]
	ds_read2_b64 v[168:171], v87 offset1:4
	ds_read2_b64 v[180:183], v87 offset0:8 offset1:12
	ds_read_b128 v[184:187], v137 offset:35072
	v_add_u32_e32 v141, 0x2800, v136
	ds_read2_b64 v[188:191], v141 offset0:192 offset1:196
	ds_read_b128 v[200:203], v139 offset:23296
	ds_read_b64 v[142:143], v166 offset:32768
	ds_read2_b64 v[212:215], v141 offset0:200 offset1:204
	ds_read_b64 v[216:217], v138 offset:32768
	s_waitcnt lgkmcnt(11)
	v_mfma_f32_16x16x32_bf16 v[38:41], v[152:155], v[4:7], v[38:41]
	ds_read_b128 v[152:155], v167 offset:23296
	v_lshl_add_u64 v[24:25], v[14:15], 0, s[14:15]
	s_waitcnt lgkmcnt(11)
	v_lshlrev_b32_e32 v14, 16, v204
	v_and_b32_e32 v15, 0xffff0000, v204
	v_lshlrev_b32_e32 v42, 16, v205
	v_and_b32_e32 v43, 0xffff0000, v205
	s_waitcnt lgkmcnt(9)
	v_pk_fma_f32 v[50:51], v[50:51], v[210:211], v[42:43]
	v_pk_fma_f32 v[48:49], v[48:49], v[208:209], v[14:15]
	v_add_u32_e32 v138, 0x3000, v136
	ds_read2_b64 v[208:211], v138 offset0:224 offset1:228
	ds_read2_b64 v[220:223], v138 offset0:232 offset1:236
	s_waitcnt lgkmcnt(10)
	v_mfma_f32_16x16x32_bf16 v[46:49], v[168:171], v[0:3], v[48:51]
	v_add_u32_e32 v138, 0x4000, v136
	ds_read_b128 v[168:171], v173 offset:23296
	v_add_co_u32_e32 v34, vcc, s69, v24
	s_waitcnt lgkmcnt(10)
	v_mfma_f32_16x16x32_bf16 v[46:49], v[180:183], v[4:7], v[46:49]
	ds_read2_b64 v[180:183], v138 offset1:4
	ds_read2_b64 v[224:227], v138 offset0:8 offset1:12
	v_addc_co_u32_e32 v35, vcc, 0, v25, vcc
	global_store_dwordx2 v[34:35], v[0:1], off nt
	v_lshlrev_b32_e32 v0, 16, v150
	v_and_b32_e32 v1, 0xffff0000, v150
	v_lshlrev_b32_e32 v8, 16, v151
	v_and_b32_e32 v9, 0xffff0000, v151
	v_cvt_pk_bf16_f32 v50, v10, v11
	v_cvt_pk_bf16_f32 v51, v12, v13
	v_cvt_pk_bf16_f32 v52, v18, v19
	v_cvt_pk_bf16_f32 v53, v20, v21
	s_waitcnt lgkmcnt(9)
	v_pk_fma_f32 v[12:13], v[12:13], v[202:203], v[8:9]
	v_pk_fma_f32 v[10:11], v[10:11], v[200:201], v[0:1]
	ds_read_b64 v[138:139], v172 offset:32768
	v_add_u32_e32 v141, 0x2800, v87
	ds_read_b128 v[148:151], v137 offset:23296
	v_mfma_f32_16x16x32_bf16 v[8:11], v[188:191], v[50:53], v[10:13]
	v_lshlrev_b32_e32 v0, 16, v178
	v_and_b32_e32 v1, 0xffff0000, v178
	v_lshlrev_b32_e32 v16, 16, v179
	ds_read_b64 v[166:167], v140 offset:32768
	ds_read2_b64 v[188:191], v141 offset0:192 offset1:196
	ds_read2_b64 v[200:203], v141 offset0:200 offset1:204
	v_and_b32_e32 v17, 0xffff0000, v179
	s_waitcnt lgkmcnt(10)
	v_pk_fma_f32 v[14:15], v[20:21], v[154:155], v[16:17]
	v_pk_fma_f32 v[12:13], v[18:19], v[152:153], v[0:1]
	v_cvt_pk_bf16_f32 v60, v38, v39
	v_cvt_pk_bf16_f32 v61, v40, v41
	s_waitcnt lgkmcnt(9)
	v_mfma_f32_16x16x32_bf16 v[12:15], v[208:211], v[50:53], v[12:15]
	v_cvt_pk_bf16_f32 v62, v46, v47
	v_cvt_pk_bf16_f32 v63, v48, v49
	global_store_dwordx2 v[34:35], v[2:3], off offset:32 nt
	global_store_dwordx2 v[34:35], v[4:5], off offset:64 nt
	global_store_dwordx2 v[34:35], v[6:7], off offset:96 nt
	s_waitcnt lgkmcnt(8)
	v_mfma_f32_16x16x32_bf16 v[0:3], v[220:223], v[60:63], v[12:15]
	v_add_u32_e32 v137, 0x5800, v136
	ds_read2_b64 v[152:155], v137 offset0:128 offset1:132
	v_lshlrev_b32_e32 v20, 16, v194
	v_and_b32_e32 v21, 0xffff0000, v194
	ds_read2_b64 v[176:179], v137 offset0:136 offset1:140
	v_lshlrev_b32_e32 v34, 16, v195
	v_and_b32_e32 v35, 0xffff0000, v195
	s_waitcnt lgkmcnt(9)
	v_pk_fma_f32 v[6:7], v[40:41], v[170:171], v[34:35]
	v_pk_fma_f32 v[4:5], v[38:39], v[168:169], v[20:21]
	v_add_u32_e32 v137, 0x6000, v136
	ds_read2_b64 v[168:171], v137 offset0:160 offset1:164
	ds_read2_b64 v[192:195], v137 offset0:168 offset1:172
	s_waitcnt lgkmcnt(10)
	v_mfma_f32_16x16x32_bf16 v[4:7], v[180:183], v[50:53], v[4:7]
	v_add_u32_e32 v137, 0x6800, v136
	ds_read2_b64 v[180:183], v137 offset0:192 offset1:196
	ds_read2_b64 v[208:211], v137 offset0:200 offset1:204
	s_waitcnt lgkmcnt(11)
	v_mfma_f32_16x16x32_bf16 v[4:7], v[224:227], v[60:63], v[4:7]
	v_lshlrev_b32_e32 v38, 16, v206
	v_and_b32_e32 v39, 0xffff0000, v206
	v_lshlrev_b32_e32 v40, 16, v207
	v_and_b32_e32 v41, 0xffff0000, v207
	s_waitcnt lgkmcnt(9)
	v_pk_fma_f32 v[14:15], v[48:49], v[150:151], v[40:41]
	v_pk_fma_f32 v[12:13], v[46:47], v[148:149], v[38:39]
	v_add_co_u32_e32 v20, vcc, s70, v24
	s_waitcnt lgkmcnt(7)
	v_mfma_f32_16x16x32_bf16 v[12:15], v[188:191], v[50:53], v[12:15]
	v_addc_co_u32_e32 v21, vcc, 0, v25, vcc
	global_store_dwordx2 v[20:21], v[50:51], off nt
	global_store_dwordx2 v[20:21], v[52:53], off offset:32 nt
	global_store_dwordx2 v[20:21], v[60:61], off offset:64 nt
	global_store_dwordx2 v[20:21], v[62:63], off offset:96 nt
	s_waitcnt lgkmcnt(6)
	v_mfma_f32_16x16x32_bf16 v[12:15], v[200:203], v[60:63], v[12:15]
	v_lshlrev_b32_e32 v20, 16, v216
	v_mfma_f32_16x16x32_bf16 v[8:11], v[212:215], v[60:63], v[8:11]
	v_and_b32_e32 v21, 0xffff0000, v216
	v_lshlrev_b32_e32 v28, 16, v217
	v_and_b32_e32 v29, 0xffff0000, v217
	v_cvt_pk_bf16_f32 v18, v0, v1
	v_cvt_pk_bf16_f32 v19, v2, v3
	s_nop 2
	v_cvt_pk_bf16_f32 v16, v8, v9
	v_cvt_pk_bf16_f32 v17, v10, v11
	v_pk_fma_f32 v[10:11], v[10:11], v[158:159], v[28:29]
	v_pk_fma_f32 v[8:9], v[8:9], v[156:157], v[20:21]
	s_waitcnt lgkmcnt(5)
	s_nop 0
	v_mfma_f32_16x16x32_bf16 v[8:11], v[152:155], v[16:19], v[8:11]
	v_cvt_pk_bf16_f32 v48, v4, v5
	v_cvt_pk_bf16_f32 v49, v6, v7
	v_cvt_pk_bf16_f32 v50, v12, v13
	v_cvt_pk_bf16_f32 v51, v14, v15
	v_lshlrev_b32_e32 v20, 16, v142
	v_and_b32_e32 v21, 0xffff0000, v142
	s_waitcnt lgkmcnt(4)
	v_mfma_f32_16x16x32_bf16 v[40:43], v[176:179], v[48:51], v[8:11]
	v_fma_f32 v0, v0, v196, v20
	v_fma_f32 v1, v1, v197, v21
	v_add_co_u32_e32 v20, vcc, s71, v24
	v_lshlrev_b32_e32 v8, 16, v143
	v_and_b32_e32 v9, 0xffff0000, v143
	v_pk_fma_f32 v[2:3], v[2:3], v[198:199], v[8:9]
	s_waitcnt lgkmcnt(3)
	s_nop 0
	v_mfma_f32_16x16x32_bf16 v[0:3], v[168:171], v[16:19], v[0:3]
	v_addc_co_u32_e32 v21, vcc, 0, v25, vcc
	s_waitcnt lgkmcnt(2)
	v_mfma_f32_16x16x32_bf16 v[36:39], v[192:195], v[48:51], v[0:3]
	v_lshlrev_b32_e32 v8, 16, v138
	s_nop 2
	v_and_b32_e32 v9, 0xffff0000, v138
	v_lshlrev_b32_e32 v10, 16, v139
	v_and_b32_e32 v11, 0xffff0000, v139
	v_pk_fma_f32 v[6:7], v[6:7], v[162:163], v[10:11]
	v_pk_fma_f32 v[4:5], v[4:5], v[160:161], v[8:9]
	v_add_u32_e32 v23, 0x5800, v87
	ds_read2_b64 v[8:11], v23 offset0:128 offset1:132
	s_waitcnt lgkmcnt(2)
	v_mfma_f32_16x16x32_bf16 v[4:7], v[180:183], v[16:19], v[4:7]
	global_store_dwordx2 v[20:21], v[16:17], off nt
	s_waitcnt lgkmcnt(1)
	v_mfma_f32_16x16x32_bf16 v[44:47], v[208:211], v[48:51], v[4:7]
	ds_read2_b64 v[0:3], v23 offset0:136 offset1:140
	global_store_dwordx2 v[20:21], v[18:19], off offset:32 nt
	global_store_dwordx2 v[20:21], v[48:49], off offset:64 nt
	global_store_dwordx2 v[20:21], v[50:51], off offset:96 nt
	s_nop 0
	v_lshlrev_b32_e32 v4, 16, v166
	v_and_b32_e32 v5, 0xffff0000, v166
	v_lshlrev_b32_e32 v6, 16, v167
	v_and_b32_e32 v7, 0xffff0000, v167
	v_pk_fma_f32 v[6:7], v[14:15], v[186:187], v[6:7]
	v_pk_fma_f32 v[4:5], v[12:13], v[184:185], v[4:5]
	s_nop 0
	s_waitcnt lgkmcnt(1)
	v_mfma_f32_16x16x32_bf16 v[4:7], v[8:11], v[16:19], v[4:7]
	s_waitcnt lgkmcnt(0)
	v_mfma_f32_16x16x32_bf16 v[48:51], v[0:3], v[48:51], v[4:7]
